# NSA selected both-block fast path rescheduled: softmax of tile pair interleaved with QK / PV MFMAs of the other tiles (MFMA-VALU interleave)
# baseline (speedup 1.0000x reference)
.LBB0_363:
	s_andn2_saveexec_b64 s[2:3], s[62:63]
	s_cbranch_execz .LBB0_369
	v_readfirstlane_b32 s1, v176
	s_add_i32 s0, s68, 0x7f
	s_nop 0
	s_cmp_le_i32 s0, s1
	s_cbranch_scc0 .Lnsa_both_slow
	v_add3_u32 v1, s90, v151, v152
	v_add3_u32 v179, s90, v154, v155
	ds_read_b128 v[180:183], v1
	ds_read_b128 v[184:187], v1 offset:32
	ds_read_b128 v[188:191], v1 offset:64
	ds_read_b128 v[192:195], v1 offset:96
	ds_read_b128 v[196:199], v1 offset:4608
	ds_read_b128 v[200:203], v1 offset:4640
	ds_read_b128 v[204:207], v1 offset:4672
	ds_read_b128 v[208:211], v1 offset:4704
	ds_read_b128 v[212:215], v1 offset:9216
	ds_read_b128 v[216:219], v1 offset:9248
	ds_read_b128 v[236:239], v1 offset:9280
	ds_read_b128 v[240:243], v1 offset:9312
	ds_read_b128 v[244:247], v1 offset:13824
	ds_read_b128 v[248:251], v1 offset:13856
	v_mov_b32_e32 v220, s87
	v_cndmask_b32_e64 v142, v234, -v220, vcc
	v_cndmask_b32_e64 v144, v234, -v220, s[50:51]
	v_mov_b32_e32 v168, 0x3e38aa3b
	s_waitcnt lgkmcnt(13)
	v_mfma_f32_32x32x16_bf16 v[34:49], v[180:183], v[98:101], 0
	s_waitcnt lgkmcnt(12)
	v_mfma_f32_32x32x16_bf16 v[34:49], v[184:187], v[102:105], v[34:49]
	ds_read_b128 v[180:183], v1 offset:13888
	ds_read_b128 v[184:187], v1 offset:13920
	s_waitcnt lgkmcnt(13)
	v_mfma_f32_32x32x16_bf16 v[34:49], v[188:191], v[106:109], v[34:49]
	s_waitcnt lgkmcnt(12)
	v_mfma_f32_32x32x16_bf16 v[34:49], v[192:195], v[110:113], v[34:49]
	s_waitcnt lgkmcnt(11)
	v_mfma_f32_32x32x16_bf16 v[50:65], v[196:199], v[98:101], 0
	s_waitcnt lgkmcnt(10)
	v_mfma_f32_32x32x16_bf16 v[50:65], v[200:203], v[102:105], v[50:65]
	s_waitcnt lgkmcnt(9)
	v_mfma_f32_32x32x16_bf16 v[50:65], v[204:207], v[106:109], v[50:65]
	s_waitcnt lgkmcnt(8)
	v_mfma_f32_32x32x16_bf16 v[50:65], v[208:211], v[110:113], v[50:65]
	ds_read_b64_tr_b16 v[188:189], v179 offset:18432
	ds_read_b64_tr_b16 v[190:191], v179 offset:19584
	ds_read_b64_tr_b16 v[192:193], v179 offset:18496
	ds_read_b64_tr_b16 v[194:195], v179 offset:19648
	ds_read_b64_tr_b16 v[196:197], v179 offset:20736
	ds_read_b64_tr_b16 v[198:199], v179 offset:21888
	ds_read_b64_tr_b16 v[200:201], v179 offset:20800
	s_waitcnt lgkmcnt(14)
	ds_read_b64_tr_b16 v[202:203], v179 offset:21952
	s_waitcnt lgkmcnt(14)
	ds_read_b64_tr_b16 v[204:205], v179 offset:23040
	s_waitcnt lgkmcnt(14)
	ds_read_b64_tr_b16 v[206:207], v179 offset:24192
	s_waitcnt lgkmcnt(14)
	ds_read_b64_tr_b16 v[208:209], v179 offset:23104
	s_waitcnt lgkmcnt(14)
	ds_read_b64_tr_b16 v[210:211], v179 offset:24256
	v_mov_b64_e32 v[220:221], 0
	v_pk_fma_f32 v[34:35], v[34:35], v[168:169], v[142:143] op_sel_hi:[1,0,0]
	v_pk_fma_f32 v[36:37], v[36:37], v[168:169], v[142:143] op_sel_hi:[1,0,0]
	v_pk_fma_f32 v[38:39], v[38:39], v[168:169], v[142:143] op_sel_hi:[1,0,0]
	v_mfma_f32_32x32x16_bf16 v[66:81], v[212:215], v[98:101], 0
	v_pk_fma_f32 v[40:41], v[40:41], v[168:169], v[142:143] op_sel_hi:[1,0,0]
	v_pk_fma_f32 v[42:43], v[42:43], v[168:169], v[142:143] op_sel_hi:[1,0,0]
	v_pk_fma_f32 v[44:45], v[44:45], v[168:169], v[142:143] op_sel_hi:[1,0,0]
	v_pk_fma_f32 v[46:47], v[46:47], v[168:169], v[142:143] op_sel_hi:[1,0,0]
	v_pk_fma_f32 v[48:49], v[48:49], v[168:169], v[142:143] op_sel_hi:[1,0,0]
	v_mfma_f32_32x32x16_bf16 v[66:81], v[216:219], v[102:105], v[66:81]
	v_exp_f32_e32 v34, v34
	v_exp_f32_e32 v35, v35
	v_exp_f32_e32 v36, v36
	v_exp_f32_e32 v37, v37
	v_exp_f32_e32 v38, v38
	v_mfma_f32_32x32x16_bf16 v[66:81], v[236:239], v[106:109], v[66:81]
	v_exp_f32_e32 v39, v39
	v_exp_f32_e32 v40, v40
	v_exp_f32_e32 v41, v41
	v_exp_f32_e32 v42, v42
	v_exp_f32_e32 v43, v43
	v_mfma_f32_32x32x16_bf16 v[66:81], v[240:243], v[110:113], v[66:81]
	v_exp_f32_e32 v44, v44
	v_exp_f32_e32 v45, v45
	v_exp_f32_e32 v46, v46
	v_exp_f32_e32 v47, v47
	v_exp_f32_e32 v48, v48
	s_waitcnt lgkmcnt(14)
	ds_read_b64_tr_b16 v[212:213], v179 offset:25344
	s_waitcnt lgkmcnt(14)
	ds_read_b64_tr_b16 v[214:215], v179 offset:26496
	s_waitcnt lgkmcnt(14)
	ds_read_b64_tr_b16 v[216:217], v179 offset:25408
	s_waitcnt lgkmcnt(14)
	ds_read_b64_tr_b16 v[218:219], v179 offset:26560
	v_exp_f32_e32 v49, v49
	v_pk_fma_f32 v[50:51], v[50:51], v[168:169], v[142:143] op_sel_hi:[1,0,0]
	v_pk_fma_f32 v[52:53], v[52:53], v[168:169], v[142:143] op_sel_hi:[1,0,0]
	v_pk_fma_f32 v[54:55], v[54:55], v[168:169], v[142:143] op_sel_hi:[1,0,0]
	v_pk_fma_f32 v[56:57], v[56:57], v[168:169], v[142:143] op_sel_hi:[1,0,0]
	v_mfma_f32_32x32x16_bf16 v[82:97], v[244:247], v[98:101], 0
	v_pk_fma_f32 v[58:59], v[58:59], v[168:169], v[142:143] op_sel_hi:[1,0,0]
	v_pk_fma_f32 v[60:61], v[60:61], v[168:169], v[142:143] op_sel_hi:[1,0,0]
	v_pk_fma_f32 v[62:63], v[62:63], v[168:169], v[142:143] op_sel_hi:[1,0,0]
	v_pk_fma_f32 v[64:65], v[64:65], v[168:169], v[142:143] op_sel_hi:[1,0,0]
	v_exp_f32_e32 v50, v50
	v_mfma_f32_32x32x16_bf16 v[82:97], v[248:251], v[102:105], v[82:97]
	v_exp_f32_e32 v51, v51
	v_exp_f32_e32 v52, v52
	v_exp_f32_e32 v53, v53
	v_exp_f32_e32 v54, v54
	v_exp_f32_e32 v55, v55
	v_mfma_f32_32x32x16_bf16 v[82:97], v[180:183], v[106:109], v[82:97]
	v_exp_f32_e32 v56, v56
	v_exp_f32_e32 v57, v57
	v_exp_f32_e32 v58, v58
	v_exp_f32_e32 v59, v59
	v_exp_f32_e32 v60, v60
	v_mfma_f32_32x32x16_bf16 v[82:97], v[184:187], v[110:113], v[82:97]
	v_exp_f32_e32 v61, v61
	v_exp_f32_e32 v62, v62
	v_exp_f32_e32 v63, v63
	v_exp_f32_e32 v64, v64
	v_exp_f32_e32 v65, v65
	v_pk_add_f32 v[220:221], v[34:35], v[220:221]
	v_pk_add_f32 v[220:221], v[36:37], v[220:221]
	v_pk_add_f32 v[220:221], v[38:39], v[220:221]
	v_pk_add_f32 v[220:221], v[40:41], v[220:221]
	v_pk_add_f32 v[220:221], v[42:43], v[220:221]
	v_pk_add_f32 v[220:221], v[44:45], v[220:221]
	v_pk_add_f32 v[220:221], v[46:47], v[220:221]
	v_pk_add_f32 v[220:221], v[48:49], v[220:221]
	v_cvt_pk_bf16_f32 v34, v34, v35
	v_cvt_pk_bf16_f32 v35, v36, v37
	v_cvt_pk_bf16_f32 v36, v38, v39
	v_cvt_pk_bf16_f32 v37, v40, v41
	v_cvt_pk_bf16_f32 v42, v42, v43
	v_cvt_pk_bf16_f32 v43, v44, v45
	v_cvt_pk_bf16_f32 v44, v46, v47
	v_cvt_pk_bf16_f32 v45, v48, v49
	s_waitcnt lgkmcnt(14)
	ds_read_b64_tr_b16 v[236:237], v179 offset:27648
	s_waitcnt lgkmcnt(14)
	ds_read_b64_tr_b16 v[238:239], v179 offset:28800
	s_waitcnt lgkmcnt(14)
	ds_read_b64_tr_b16 v[240:241], v179 offset:27712
	s_waitcnt lgkmcnt(14)
	ds_read_b64_tr_b16 v[242:243], v179 offset:28864
	s_waitcnt lgkmcnt(14)
	ds_read_b64_tr_b16 v[244:245], v179 offset:29952
	s_waitcnt lgkmcnt(14)
	ds_read_b64_tr_b16 v[246:247], v179 offset:31104
	s_waitcnt lgkmcnt(14)
	ds_read_b64_tr_b16 v[248:249], v179 offset:30016
	s_waitcnt lgkmcnt(14)
	ds_read_b64_tr_b16 v[250:251], v179 offset:31168
	s_waitcnt lgkmcnt(14)
	ds_read_b64_tr_b16 v[180:181], v179 offset:32256
	s_waitcnt lgkmcnt(14)
	ds_read_b64_tr_b16 v[182:183], v179 offset:33408
	s_waitcnt lgkmcnt(14)
	ds_read_b64_tr_b16 v[184:185], v179 offset:32320
	s_waitcnt lgkmcnt(14)
	ds_read_b64_tr_b16 v[186:187], v179 offset:33472
	v_pk_add_f32 v[220:221], v[50:51], v[220:221]
	v_pk_add_f32 v[220:221], v[52:53], v[220:221]
	v_mfma_f32_32x32x16_bf16 v[18:33], v[188:191], v[34:37], v[18:33]
	v_pk_add_f32 v[220:221], v[54:55], v[220:221]
	v_pk_add_f32 v[220:221], v[56:57], v[220:221]
	v_pk_add_f32 v[220:221], v[58:59], v[220:221]
	v_mfma_f32_32x32x16_bf16 v[2:17], v[192:195], v[34:37], v[2:17]
	v_pk_add_f32 v[220:221], v[60:61], v[220:221]
	v_pk_add_f32 v[220:221], v[62:63], v[220:221]
	v_pk_add_f32 v[220:221], v[64:65], v[220:221]
	v_cvt_pk_bf16_f32 v50, v50, v51
	v_mfma_f32_32x32x16_bf16 v[18:33], v[196:199], v[42:45], v[18:33]
	v_cvt_pk_bf16_f32 v51, v52, v53
	v_cvt_pk_bf16_f32 v52, v54, v55
	v_cvt_pk_bf16_f32 v53, v56, v57
	v_mfma_f32_32x32x16_bf16 v[2:17], v[200:203], v[42:45], v[2:17]
	v_cvt_pk_bf16_f32 v58, v58, v59
	v_cvt_pk_bf16_f32 v59, v60, v61
	v_cvt_pk_bf16_f32 v60, v62, v63
	v_cvt_pk_bf16_f32 v61, v64, v65
	s_waitcnt lgkmcnt(14)
	ds_read_b64_tr_b16 v[188:189], v179 offset:34560
	s_waitcnt lgkmcnt(14)
	ds_read_b64_tr_b16 v[190:191], v179 offset:35712
	s_waitcnt lgkmcnt(14)
	ds_read_b64_tr_b16 v[192:193], v179 offset:34624
	s_waitcnt lgkmcnt(14)
	ds_read_b64_tr_b16 v[194:195], v179 offset:35776
	v_pk_fma_f32 v[66:67], v[66:67], v[168:169], v[144:145] op_sel_hi:[1,0,0]
	v_pk_fma_f32 v[68:69], v[68:69], v[168:169], v[144:145] op_sel_hi:[1,0,0]
	v_pk_fma_f32 v[70:71], v[70:71], v[168:169], v[144:145] op_sel_hi:[1,0,0]
	v_pk_fma_f32 v[72:73], v[72:73], v[168:169], v[144:145] op_sel_hi:[1,0,0]
	v_mfma_f32_32x32x16_bf16 v[18:33], v[204:207], v[50:53], v[18:33]
	v_pk_fma_f32 v[74:75], v[74:75], v[168:169], v[144:145] op_sel_hi:[1,0,0]
	v_pk_fma_f32 v[76:77], v[76:77], v[168:169], v[144:145] op_sel_hi:[1,0,0]
	v_pk_fma_f32 v[78:79], v[78:79], v[168:169], v[144:145] op_sel_hi:[1,0,0]
	v_pk_fma_f32 v[80:81], v[80:81], v[168:169], v[144:145] op_sel_hi:[1,0,0]
	v_exp_f32_e32 v66, v66
	v_exp_f32_e32 v67, v67
	v_exp_f32_e32 v68, v68
	v_exp_f32_e32 v69, v69
	v_exp_f32_e32 v70, v70
	v_exp_f32_e32 v71, v71
	v_exp_f32_e32 v72, v72
	v_mfma_f32_32x32x16_bf16 v[2:17], v[208:211], v[50:53], v[2:17]
	v_exp_f32_e32 v73, v73
	v_exp_f32_e32 v74, v74
	v_exp_f32_e32 v75, v75
	v_exp_f32_e32 v76, v76
	v_exp_f32_e32 v77, v77
	v_exp_f32_e32 v78, v78
	v_exp_f32_e32 v79, v79
	v_exp_f32_e32 v80, v80
	v_exp_f32_e32 v81, v81
	v_pk_fma_f32 v[82:83], v[82:83], v[168:169], v[144:145] op_sel_hi:[1,0,0]
	v_pk_fma_f32 v[84:85], v[84:85], v[168:169], v[144:145] op_sel_hi:[1,0,0]
	v_mfma_f32_32x32x16_bf16 v[18:33], v[212:215], v[58:61], v[18:33]
	v_pk_fma_f32 v[86:87], v[86:87], v[168:169], v[144:145] op_sel_hi:[1,0,0]
	v_pk_fma_f32 v[88:89], v[88:89], v[168:169], v[144:145] op_sel_hi:[1,0,0]
	v_pk_fma_f32 v[90:91], v[90:91], v[168:169], v[144:145] op_sel_hi:[1,0,0]
	v_pk_fma_f32 v[92:93], v[92:93], v[168:169], v[144:145] op_sel_hi:[1,0,0]
	v_pk_fma_f32 v[94:95], v[94:95], v[168:169], v[144:145] op_sel_hi:[1,0,0]
	v_pk_fma_f32 v[96:97], v[96:97], v[168:169], v[144:145] op_sel_hi:[1,0,0]
	v_exp_f32_e32 v82, v82
	v_exp_f32_e32 v83, v83
	v_exp_f32_e32 v84, v84
	v_exp_f32_e32 v85, v85
	v_exp_f32_e32 v86, v86
	v_mfma_f32_32x32x16_bf16 v[2:17], v[216:219], v[58:61], v[2:17]
	v_exp_f32_e32 v87, v87
	v_exp_f32_e32 v88, v88
	v_exp_f32_e32 v89, v89
	v_exp_f32_e32 v90, v90
	v_exp_f32_e32 v91, v91
	v_exp_f32_e32 v92, v92
	v_exp_f32_e32 v93, v93
	v_exp_f32_e32 v94, v94
	v_exp_f32_e32 v95, v95
	v_exp_f32_e32 v96, v96
	v_exp_f32_e32 v97, v97
	v_pk_add_f32 v[220:221], v[66:67], v[220:221]
	v_pk_add_f32 v[220:221], v[68:69], v[220:221]
	v_pk_add_f32 v[220:221], v[70:71], v[220:221]
	v_pk_add_f32 v[220:221], v[72:73], v[220:221]
	v_pk_add_f32 v[220:221], v[74:75], v[220:221]
	v_pk_add_f32 v[220:221], v[76:77], v[220:221]
	v_pk_add_f32 v[220:221], v[78:79], v[220:221]
	v_pk_add_f32 v[220:221], v[80:81], v[220:221]
	v_cvt_pk_bf16_f32 v66, v66, v67
	v_cvt_pk_bf16_f32 v67, v68, v69
	v_cvt_pk_bf16_f32 v68, v70, v71
	v_cvt_pk_bf16_f32 v69, v72, v73
	v_cvt_pk_bf16_f32 v74, v74, v75
	v_cvt_pk_bf16_f32 v75, v76, v77
	v_cvt_pk_bf16_f32 v76, v78, v79
	v_cvt_pk_bf16_f32 v77, v80, v81
	v_pk_add_f32 v[220:221], v[82:83], v[220:221]
	v_pk_add_f32 v[220:221], v[84:85], v[220:221]
	s_waitcnt lgkmcnt(14)
	v_mfma_f32_32x32x16_bf16 v[18:33], v[236:239], v[66:69], v[18:33]
	v_pk_add_f32 v[220:221], v[86:87], v[220:221]
	v_pk_add_f32 v[220:221], v[88:89], v[220:221]
	v_pk_add_f32 v[220:221], v[90:91], v[220:221]
	s_waitcnt lgkmcnt(12)
	v_mfma_f32_32x32x16_bf16 v[2:17], v[240:243], v[66:69], v[2:17]
	v_pk_add_f32 v[220:221], v[92:93], v[220:221]
	v_pk_add_f32 v[220:221], v[94:95], v[220:221]
	v_pk_add_f32 v[220:221], v[96:97], v[220:221]
	v_cvt_pk_bf16_f32 v82, v82, v83
	s_waitcnt lgkmcnt(10)
	v_mfma_f32_32x32x16_bf16 v[18:33], v[244:247], v[74:77], v[18:33]
	v_cvt_pk_bf16_f32 v83, v84, v85
	v_cvt_pk_bf16_f32 v84, v86, v87
	v_cvt_pk_bf16_f32 v85, v88, v89
	s_waitcnt lgkmcnt(8)
	v_mfma_f32_32x32x16_bf16 v[2:17], v[248:251], v[74:77], v[2:17]
	v_cvt_pk_bf16_f32 v90, v90, v91
	v_cvt_pk_bf16_f32 v91, v92, v93
	v_cvt_pk_bf16_f32 v92, v94, v95
	v_cvt_pk_bf16_f32 v93, v96, v97
	v_add_f32_e32 v143, v143, v220
	v_add_f32_e32 v143, v143, v221
	s_waitcnt lgkmcnt(6)
	v_mfma_f32_32x32x16_bf16 v[18:33], v[180:183], v[82:85], v[18:33]
	s_waitcnt lgkmcnt(4)
	v_mfma_f32_32x32x16_bf16 v[2:17], v[184:187], v[82:85], v[2:17]
	s_waitcnt lgkmcnt(2)
	v_mfma_f32_32x32x16_bf16 v[18:33], v[188:191], v[90:93], v[18:33]
	s_waitcnt lgkmcnt(0)
	v_mfma_f32_32x32x16_bf16 v[2:17], v[192:195], v[90:93], v[2:17]
	s_branch .LBB0_369
